# FFN weight conversion loop: next tile loads kept in flight across barrier (cur<-nxt copy deferred to next iteration top)
# speedup vs baseline: 1.0061x; 1.0061x over previous
; __device__ __forceinline__ void convert_layer_weights(const Params& p, uchar* sm, int i, bool mixer, bool ffn) {
;     ...
;     f32x4 cur[2], nxt[2];
;     int it = bid;
;     if (it < n_all) cvt_load(job(it), tid, cur);
;     for (; it < n_all; it += gridDim.x) {
;         const CvtJob jb = job(it);
;         cvt_to_lds(tid, cur, scr);
;         if (it + (int)gridDim.x < n_all) cvt_load(job(it + gridDim.x), tid, nxt);
.LBB0_165:
	s_or_b64 exec, exec, s[10:11]
	s_bitcmp1_b32 s42, 0
	s_cselect_b64 s[10:11], -1, 0
	s_movk_i32 s8, 0x104
	v_mul_lo_u32 v5, v20, s8
	v_lshlrev_b32_e32 v2, 3, v4
	s_and_b64 s[8:9], s[10:11], exec
	v_ashrrev_i32_e32 v22, 3, v4
	v_and_b32_e32 v4, 56, v2
	s_movk_i32 s8, 0x1820
	v_mul_u32_u24_e32 v2, 0x104, v4
	v_lshlrev_b32_e32 v6, 2, v22
	s_cselect_b32 s25, s8, 0xc00
	v_readlane_b32 s8, v255, 30
	v_readlane_b32 s9, v255, 32
	v_lshl_add_u32 v3, v1, 2, 0
	v_add3_u32 v23, 0, v2, v6
	s_cselect_b32 s9, s8, s9
	v_readlane_b32 s8, v255, 29
	v_readlane_b32 s12, v255, 31
	v_add_u32_e32 v21, 32, v20
	s_cselect_b32 s8, s8, s12
	s_xor_b64 s[10:11], s[10:11], -1
	v_add_u32_e32 v24, v3, v5
	v_lshlrev_b32_e32 v18, 1, v4
	s_waitcnt vmcnt(0)
	v_mov_b32_e32 v2, v14
	v_mov_b32_e32 v3, v15
	v_mov_b32_e32 v4, v16
	v_mov_b32_e32 v5, v17
	v_mov_b32_e32 v6, v10
	v_mov_b32_e32 v7, v11
	v_mov_b32_e32 v8, v12
	v_mov_b32_e32 v9, v13
	s_branch .LBB0_168

; __device__ __forceinline__ unsigned pk2(float lo, float hi) { unsigned r; asm("v_cvt_pk_bf16_f32 %0, %1, %2" : "=v"(r) : "v"(lo), "v"(hi)); return r; }
; __device__ __forceinline__ void cvt_store(const CvtJob& jb, int tid, const float* scr) {
;     const int nkt = jb.K / 64, nb = jb.tile / nkt, kb = jb.tile % nkt, n0 = nb * 64, k0 = kb * 64;
;     const int nl = tid >> 3, kc = tid & 7; const float* sp = scr + (kc * 8) * 65 + nl;
;     u32x4 o; o.x = pk2(sp[0], sp[65]); o.y = pk2(sp[2 * 65], sp[3 * 65]); o.z = pk2(sp[4 * 65], sp[5 * 65]); o.w = pk2(sp[6 * 65], sp[7 * 65]);
;     *(u32x4*)(jb.Wt + (size_t)(n0 + nl) * jb.ldw + k0 + kc * 8) = o;
; __device__ __forceinline__ void convert_layer_weights(const Params& p, uchar* sm, int i, bool mixer, bool ffn) {
;     ...
;         __syncthreads();
;         cvt_store(jb, tid, scr);
;         __syncthreads();
;         cur[0] = nxt[0]; cur[1] = nxt[1];
.LBB0_167:
	s_abs_i32 s20, s26
	v_cvt_f32_u32_e32 v10, s20
	s_sub_i32 s21, 0, s20
	s_abs_i32 s19, s13
	s_xor_b32 s18, s13, s26
	v_rcp_iflag_f32_e32 v10, v10
	s_ashr_i32 s18, s18, 31
	s_waitcnt lgkmcnt(0)
	s_barrier
	v_mul_f32_e32 v10, 0x4f7ffffe, v10
	v_cvt_u32_f32_e32 v10, v10
	ds_read2_b32 v[12:13], v23 offset0:130 offset1:195
	v_add_u32_e32 v14, 0x400, v23
	v_readfirstlane_b32 s22, v10
	s_mul_i32 s21, s21, s22
	s_mul_hi_u32 s21, s22, s21
	s_add_i32 s22, s22, s21
	s_mul_hi_u32 s21, s19, s22
	s_mul_i32 s22, s21, s20
	s_sub_i32 s19, s19, s22
	s_add_i32 s22, s21, 1
	s_sub_i32 s23, s19, s20
	s_cmp_ge_u32 s19, s20
	s_cselect_b32 s21, s22, s21
	s_cselect_b32 s19, s23, s19
	s_add_i32 s22, s21, 1
	s_cmp_ge_u32 s19, s20
	s_cselect_b32 s19, s22, s21
	s_xor_b32 s19, s19, s18
	s_sub_i32 s19, s19, s18
	ds_read2_b32 v[10:11], v23 offset1:65
	s_mul_i32 s18, s19, s26
	s_waitcnt lgkmcnt(0)
	v_cvt_pk_bf16_f32 v10, v10, v11
	v_cvt_pk_bf16_f32 v11, v12, v13
	ds_read2_b32 v[12:13], v14 offset0:4 offset1:69
	ds_read2_b32 v[14:15], v14 offset0:134 offset1:199
	s_sub_i32 s13, s13, s18
	s_waitcnt lgkmcnt(1)
	v_cvt_pk_bf16_f32 v12, v12, v13
	s_waitcnt lgkmcnt(0)
	v_cvt_pk_bf16_f32 v13, v14, v15
	v_lshl_add_u32 v14, s19, 6, v22
	s_lshl_b32 s18, s13, 6
	v_mad_i64_i32 v[14:15], s[12:13], s12, v14, 0
	v_lshl_add_u64 v[14:15], v[14:15], 1, s[14:15]
	s_ashr_i32 s19, s18, 31
	v_lshl_add_u64 v[14:15], s[18:19], 1, v[14:15]
	v_mov_b32_e32 v19, v0
	v_lshl_add_u64 v[14:15], v[14:15], 0, v[18:19]
	global_store_dwordx4 v[14:15], v[10:13], off
	s_andn2_b64 vcc, exec, s[16:17]
	s_barrier
	s_cbranch_vccz .LBB0_186

; __device__ __forceinline__ void cvt_to_lds(int tid, const f32x4 (&v)[2], float* scr) {
;     const int n4 = (tid & 15) * 4, kk0 = tid >> 4;
; #pragma unroll
;     for (int i = 0; i < 2; ++i) { float* d = scr + (kk0 + 32 * i) * 65 + n4; d[0] = v[i][0]; d[1] = v[i][1]; d[2] = v[i][2]; d[3] = v[i][3]; }
; }
; __device__ __forceinline__ void convert_layer_weights(const Params& p, uchar* sm, int i, bool mixer, bool ffn) {
;     ...
;     for (; it < n_all; it += gridDim.x) {
;         const CvtJob jb = job(it);
;         cvt_to_lds(tid, cur, scr);
;         if (it + (int)gridDim.x < n_all) cvt_load(job(it + gridDim.x), tid, nxt);
.LBB0_171:
	s_add_i32 s24, s24, s94
	s_cmpk_gt_i32 s24, 0x83f
	s_waitcnt vmcnt(0)
	v_mov_b32_e32 v14, v2
	v_mov_b32_e32 v15, v3
	v_mov_b32_e32 v16, v4
	v_mov_b32_e32 v17, v5
	v_mov_b32_e32 v10, v6
	v_mov_b32_e32 v11, v7
	v_mov_b32_e32 v12, v8
	v_mov_b32_e32 v13, v9
	ds_write2_b32 v24, v14, v15 offset1:1
	ds_write2_b32 v24, v16, v17 offset0:2 offset1:3
	v_add_u32_e32 v14, 0x2080, v24
	s_cselect_b64 s[16:17], -1, 0
	ds_write2_b32 v14, v10, v11 offset1:1
	v_add_u32_e32 v10, 0x2088, v24
	s_and_b64 vcc, exec, s[16:17]
	ds_write2_b32 v10, v12, v13 offset1:1
	s_cbranch_vccnz .LBB0_167
	s_cmp_lt_i32 s24, 0
	s_cbranch_scc1 .LBB0_175
	s_cmpk_lt_u32 s24, 0x580
	s_cbranch_scc1 .LBB0_176
	s_add_i32 s29, s24, 0xfffffa80
	s_movk_i32 s27, 0x400
	s_mov_b32 s28, 44
	s_mov_b64 s[20:21], 0
	s_mov_b64 s[18:19], s[0:1]
	s_branch .LBB0_177
